# ATT phase scheduled in three stages by XCD group so fewer CUs are inside MLA units at once
# speedup vs baseline: 1.0019x; 1.0011x over previous
; #define LAUNDER() int tid = tid0; asm volatile("" : "+v"(tid)); int wg = blockIdx.x; asm volatile("" : "+s"(wg)); const int lane = tid & 63, wave = __builtin_amdgcn_readfirstlane(tid >> 6), gw = wg * NWAVES + wave, NGW = G * NWAVES; (void)lane; (void)wave; (void)gw; (void)NGW
; __global__ void __launch_bounds__(NTHR, 2) fwd_kernel(Args a) {
;     ...
;         for (int stage = 0; stage < 2; ++stage) {
;         bool mla_now; { int wgs = blockIdx.x; asm volatile("" : "+s"(wgs)); mla_now = (stage == 0) != ((wgs & ATT_SWAP_MASK) != 0); }
;         if (mla_now) { LAUNDER();
;           const int n_mla = lastl ? 512 : 512 + 16;
;           for (int u = wg; u < n_mla; u += G) {
;             if (u < 512) { const int pair = 2 * (u & 7) + (u >> 8), qb = (u >> 3) & 31, b = pair >> 2, h = pair & 3; mla_unit(QM, KVM, KR, Y, b, h, b * TB + CTX + 256 * qb, 132, true, L, tid); }
;             else { const int i = u - 512, b = i >> 2, h = i & 3; mla_unit(QM, KVM, KR, Y, b, h, b * TB, 4, false, L, tid); }
;           } }
;         else {
;         { LAUNDER();
;           const int n_swa = lastl ? 1024 : 1024 + 32;
;           for (int u = (wg + 64) % G; u < n_swa; u += G) {
;             if (u < 1024) swa_unit(Z, a.in[IN_SINK] + l * 16, Y, u >> 8, (u >> 7) & 1, u & 127, 0, L, tid);
;             else { const int i = u - 1024; swa_unit(Z, a.in[IN_SINK] + l * 16, Y, i >> 3, (i >> 2) & 1, -1, i & 3, L, tid); }
;           } }
.LBB0_825:
	s_mov_b32 s100, 0
	s_mov_b32 s91, 0x50000
	s_mov_b32 s0, 0x40000
	s_mov_b32 s90, 0x30000
	s_mov_b32 s47, 0x20000
	s_or_b64 exec, exec, s[2:3]
	s_and_b64 s[2:3], s[60:61], exec
	s_movk_i32 s2, 0x210
	s_cselect_b32 s28, 0x200, s2
	s_movk_i32 s2, 0x400
	v_readlane_b32 s72, v252, 0
	s_cselect_b32 s29, s2, 0x420
	v_readlane_b32 s82, v252, 10
	v_readlane_b32 s2, v255, 17
	v_readlane_b32 s83, v252, 11
	v_readlane_b32 s3, v255, 18
	s_add_u32 s18, s82, s2
	s_addc_u32 s19, s83, s3
	v_readlane_b32 s2, v254, 63
	v_readlane_b32 s3, v255, 0
	s_lshl_b32 s56, s2, 9
	v_readlane_b32 s73, v252, 1
	v_readlane_b32 s74, v252, 2
	v_readlane_b32 s75, v252, 3
	v_readlane_b32 s76, v252, 4
	v_readlane_b32 s77, v252, 5
	v_readlane_b32 s78, v252, 6
	v_readlane_b32 s79, v252, 7
	v_readlane_b32 s80, v252, 8
	v_readlane_b32 s81, v252, 9
	v_readlane_b32 s84, v252, 12
	v_readlane_b32 s85, v252, 13
	v_readlane_b32 s86, v252, 14
	s_lshl_b64 s[2:3], s[56:57], 2
	s_mov_b32 s46, s48
	v_readlane_b32 s87, v252, 15
	s_add_u32 s30, s86, s2
	v_readlane_b32 s42, v252, 53
	v_readlane_b32 s48, v252, 55
	v_readlane_b32 s50, v252, 57
	v_readlane_b32 s72, v252, 59
	v_readlane_b32 s74, v252, 61
	v_readlane_b32 s76, v252, 63
	v_readlane_b32 s78, v253, 1
	v_readlane_b32 s80, v254, 31
	v_readlane_b32 s82, v254, 33
	v_readlane_b32 s84, v254, 35
	s_addc_u32 s31, s87, s3
	s_mov_b32 s2, 0
	s_mov_b64 s[22:23], -1
	v_readlane_b32 s43, v252, 54
	v_readlane_b32 s49, v252, 56
	v_readlane_b32 s51, v252, 58
	v_readlane_b32 s73, v252, 60
	v_readlane_b32 s75, v252, 62
	v_readlane_b32 s77, v253, 0
	v_readlane_b32 s79, v253, 2
	v_readlane_b32 s81, v254, 32
	v_readlane_b32 s83, v254, 34
	v_readlane_b32 s85, v254, 36
	v_readlane_b32 s39, v253, 53
	v_readlane_b32 s53, v253, 52
	v_readlane_b32 s86, v254, 9
	v_readlane_b32 s87, v254, 10
	s_waitcnt lgkmcnt(0)
	s_barrier
	s_branch .LBB0_827
.LBB0_826:
	s_add_i32 s100, s100, 1
	s_barrier
	s_cmp_eq_u32 s100, 3
	s_cbranch_scc1 .LBB0_980
.LBB0_827:
	s_and_b32 s3, s46, 7
	s_mul_i32 s3, s3, 3
	s_lshr_b32 s3, s3, 3
	s_cmp_eq_u32 s3, s100
	s_cbranch_scc1 .Latt_light_path
	s_cmp_gt_u32 s100, s3
	s_cselect_b32 s2, 1, 0
	s_sub_i32 s2, s100, s2
	s_cmp_eq_u32 s2, 0
	s_cselect_b32 s101, 0, s28
	s_mov_b64 s[2:3], -1
	s_branch .LBB0_881
.Latt_light_path:
	s_mov_b64 s[2:3], -1
	s_waitcnt vmcnt(7)
	v_mov_b32_e32 v2, v0
	s_mov_b32 s2, s46
	s_add_i32 s3, s2, 64
	s_ashr_i32 s2, s3, 31
	s_abs_i32 s3, s3
	s_mul_hi_u32 s4, s3, s53
	s_mul_i32 s4, s4, s39
	s_sub_i32 s3, s3, s4
	s_sub_i32 s4, s3, s39
	s_cmp_ge_u32 s3, s39
	s_cselect_b32 s3, s4, s3
	s_sub_i32 s4, s3, s39
	s_cmp_ge_u32 s3, s39
	s_cselect_b32 s3, s4, s3
	s_xor_b32 s3, s3, s2
	s_sub_i32 s8, s3, s2
	s_cmp_ge_i32 s8, s29
	s_cbranch_scc1 .LBB0_873
	v_and_b32_e32 v3, 63, v2
	v_lshlrev_b32_e32 v4, 4, v2
	v_bfe_u32 v5, v2, 5, 1
	v_cmp_gt_u32_e32 vcc, 32, v3
	v_ashrrev_i32_e32 v3, 3, v2
	v_and_b32_e32 v4, 0x70, v4
	s_waitcnt vmcnt(6)
	v_mul_lo_u32 v6, v3, s35
	v_mad_u64_u32 v[158:159], s[4:5], v3, s54, v[4:5]
	v_or_b32_e32 v6, v6, v4
	v_mul_lo_u32 v159, v3, 48
	v_lshlrev_b32_e32 v3, 2, v5
	v_lshrrev_b32_e32 v4, 2, v2
	v_and_or_b32 v4, v4, 3, v3
	v_ashrrev_i32_e32 v1, 6, v2
	v_and_b32_e32 v31, 31, v2
	v_mul_u32_u24_e32 v172, 0xc0, v4
	v_and_b32_e32 v4, 16, v2
	v_lshlrev_b32_e32 v2, 2, v2
	v_and_or_b32 v2, v2, 12, v4
	v_lshlrev_b32_e32 v173, 1, v2
	v_lshlrev_b32_e32 v30, 3, v5
	v_cndmask_b32_e64 v170, 0, 1.0, vcc
	v_add_u32_e32 v156, 0xe80, v6
	v_add_u32_e32 v171, v158, v159
	v_mov_b32_e32 v157, v33
	v_add_u32_e32 v174, 0, v158
	v_mul_u32_u24_e32 v175, 0x90, v31
	v_lshlrev_b32_e32 v160, 4, v5
	v_add_u32_e32 v176, 0xffffff7f, v3
	v_mov_b32_e32 v161, v33
	v_or_b32_e32 v177, 0x100, v31
	v_mad_u32_u24 v178, v31, s54, 0
	v_add3_u32 v179, 0, v172, v173
	s_sub_i32 s9, s3, s2
	v_sub_u32_e32 v180, 0xfffffe60, v31
	s_branch .LBB0_832

; #define LAUNDER() int tid = tid0; asm volatile("" : "+v"(tid)); int wg = blockIdx.x; asm volatile("" : "+s"(wg)); const int lane = tid & 63, wave = __builtin_amdgcn_readfirstlane(tid >> 6), gw = wg * NWAVES + wave, NGW = G * NWAVES; (void)lane; (void)wave; (void)gw; (void)NGW
; __global__ void __launch_bounds__(NTHR, 2) fwd_kernel(Args a) {
;     ...
;         if (mla_now) { LAUNDER();
;           const int n_mla = lastl ? 512 : 512 + 16;
;           for (int u = wg; u < n_mla; u += G) {
;             if (u < 512) { const int pair = 2 * (u & 7) + (u >> 8), qb = (u >> 3) & 31, b = pair >> 2, h = pair & 3; mla_unit(QM, KVM, KR, Y, b, h, b * TB + CTX + 256 * qb, 132, true, L, tid); }
;             else { const int i = u - 512, b = i >> 2, h = i & 3; mla_unit(QM, KVM, KR, Y, b, h, b * TB, 4, false, L, tid); }
.LBB0_881:
	s_and_b64 vcc, exec, s[2:3]
	s_cbranch_vccz .LBB0_826
	v_mov_b32_e32 v1, v0
	s_mov_b32 s6, s46
	s_cmp_lg_u32 s101, 0
	s_cselect_b32 s7, s21, 0
	s_add_i32 s6, s6, s7
	s_cmp_ge_i32 s6, s28
	s_cbranch_scc1 .LBB0_826
	s_lshl_b32 s7, s6, 1
	s_branch .LBB0_951

; template <int DV>
; __device__ __forceinline__ void attn_store(bf16* yrow  , const f32x16 (&o)[DV / 32], float l, int hi) {
;     ...
;             *(v4u*)(yb + 64 * d + 32 * kk) = (v4u){rx[0], ry[0], rx[1], ry[1]};
; __global__ void __launch_bounds__(NTHR, 2) fwd_kernel(Args a) {
;     ...
;           for (int u = wg; u < n_mla; u += G) {
;             if (u < 512) { const int pair = 2 * (u & 7) + (u >> 8), qb = (u >> 3) & 31, b = pair >> 2, h = pair & 3; mla_unit(QM, KVM, KR, Y, b, h, b * TB + CTX + 256 * qb, 132, true, L, tid); }
.LBB0_950:
	s_add_i32 s6, s6, s21
	s_add_i32 s7, s7, s95
	s_cmp_ge_i32 s6, s101
	s_waitcnt vmcnt(3)
	global_store_dwordx4 v[18:19], v[2:5], off offset:224
	s_cbranch_scc1 .LBB0_826
